# drop 3 grid barriers: PLE(l0)->prep(l1) independent; sgu->pool GEMM same-workgroup via in-place pool output
# speedup vs baseline: 1.0224x; 1.0093x over previous
; __global__ void __launch_bounds__(512) fwd_kernel(Params p) {
;     ...
;         if (ph + 1 < p.ph_hi && k != 3) { xcd_barrier(xbar); if (p.ph_lo < 0) grid.sync(); }
.Lmy_wgsync:
	s_waitcnt vmcnt(0)
	s_barrier
	s_branch .LBB0_9

; __global__ void __launch_bounds__(512) fwd_kernel(Params p) {
;     ...
;         case 5: S.nN = 4; S.nsub = 2; S.s0 = SubG{Z, (const bf16_t*)(ws + W_A), NIN, D, D, MODE_YA, 0, 1 << 30, 0};
;                 S.s1 = SubG{Z + 1024, (const bf16_t*)(ws + W_B), NIN, D, D, MODE_YB, 0, 1 << 30, 0}; is_gemm = true; break;
.LBB0_66:
	s_load_dwordx2 s[12:13], s[0:1], 0xb0
	s_movk_i32 s2, 0x1400
	s_add_u32 s84, s70, 0x1000
	s_addc_u32 s85, s71, 0
	s_waitcnt lgkmcnt(0)
	s_add_u32 s46, s12, 0xe80000
	s_addc_u32 s47, s13, 0
	s_add_u32 s12, s12, 0x1080000
	s_addc_u32 s13, s13, 0
	v_writelane_b32 v250, s12, 15
	s_nop 1
	v_writelane_b32 v250, s13, 16
	v_writelane_b32 v250, s2, 19
	s_mov_b32 s2, 3
	v_writelane_b32 v250, s2, 14
	s_mov_b64 s[12:13], -1
	v_writelane_b32 v250, s12, 21
	s_mov_b32 s2, 2
	s_nop 0
	v_writelane_b32 v250, s13, 22
	v_writelane_b32 v250, s2, 13

; __device__ __forceinline__ u32x4 pack8(const f32x4& v0, const f32x4& v1) { u32x4 w; w.x = cvt_pk_bf16(v0[0], v0[1]); w.y = cvt_pk_bf16(v0[2], v0[3]); w.z = cvt_pk_bf16(v1[0], v1[1]); w.w = cvt_pk_bf16(v1[2], v1[3]); return w; }
; __device__ __forceinline__ void epi_run(const Epi& E, f32x4 (&acc)[2][2][4][2], const Unit& u, int wr, int wc, int fr, int fq) {
;     ...
;     } else if (mode == MODE_POOL) {
;         f32x4 sc[2][2];
; #pragma unroll
;         for (int bj = 0; bj < 2; ++bj) { sc[bj][0] = *(const f32x4*)(E.pool_scale + col0 + bj * 128); sc[bj][1] = *(const f32x4*)(E.pool_scale + col0 + bj * 128 + 4); }
; #pragma unroll
;         for (int ai = 0; ai < 2; ++ai)
; #pragma unroll
;             for (int m = 0; m < 4; ++m)
; #pragma unroll
;                 for (int bj = 0; bj < 2; ++bj) *(u32x4*)(E.Z + (size_t)(row0 + ai * 128 + m * 16) * NIN + col0 + bj * 128) = pack8(acc[ai][bj][m][0] * sc[bj][0], acc[ai][bj][m][1] * sc[bj][1]);
.LBB0_303:
	s_andn2_b64 vcc, exec, s[8:9]
	s_cbranch_vccnz .LBB0_305
	v_readlane_b32 s8, v250, 27
	v_ashrrev_i32_e32 v213, 31, v212
	v_readlane_b32 s9, v250, 28
	v_or_b32_e32 v0, 16, v210
	s_nop 0
	v_lshl_add_u64 v[138:139], v[212:213], 2, s[8:9]
	global_load_dwordx4 v[134:137], v[138:139], off offset:16
	global_load_dwordx4 v[142:145], v[138:139], off
	s_waitcnt lgkmcnt(0)
	global_load_dwordx4 v[130:133], v[138:139], off offset:528
	s_nop 0
	global_load_dwordx4 v[138:141], v[138:139], off offset:512
	s_waitcnt vmcnt(0)
	v_pk_mul_f32 v[150:151], v[124:125], v[136:137]
	v_pk_mul_f32 v[148:149], v[128:129], v[144:145]
	v_pk_mul_f32 v[146:147], v[126:127], v[142:143]
	v_pk_mul_f32 v[152:153], v[122:123], v[134:135]
	v_cvt_pk_bf16_f32 v146, v146, v147
	v_cvt_pk_bf16_f32 v147, v148, v149
	v_cvt_pk_bf16_f32 v149, v150, v151
	s_add_u32 s8, s70, 0x1000
	s_addc_u32 s9, s71, 0
	v_mov_b64_e32 v[150:151], s[8:9]
	v_cvt_pk_bf16_f32 v148, v152, v153
	v_mad_i64_i32 v[154:155], s[8:9], v210, s69, v[150:151]
	v_lshlrev_b64 v[152:153], 1, v[212:213]
	v_lshl_add_u64 v[154:155], v[154:155], 0, v[152:153]
	global_store_dwordx4 v[154:155], v[146:149], off
	v_pk_mul_f32 v[156:157], v[116:117], v[132:133]
	v_pk_mul_f32 v[158:159], v[114:115], v[130:131]
	v_pk_mul_f32 v[148:149], v[120:121], v[140:141]
	v_pk_mul_f32 v[146:147], v[118:119], v[138:139]
	s_nop 0
	v_cvt_pk_bf16_f32 v146, v146, v147
	v_cvt_pk_bf16_f32 v147, v148, v149
	v_cvt_pk_bf16_f32 v148, v158, v159
	v_cvt_pk_bf16_f32 v149, v156, v157
	global_store_dwordx4 v[154:155], v[146:149], off offset:256
	v_pk_mul_f32 v[154:155], v[108:109], v[136:137]
	v_pk_mul_f32 v[156:157], v[106:107], v[134:135]
	v_pk_mul_f32 v[148:149], v[112:113], v[144:145]
	v_pk_mul_f32 v[146:147], v[110:111], v[142:143]
	v_pk_mul_f32 v[158:159], v[94:95], v[130:131]
	v_cvt_pk_bf16_f32 v146, v146, v147
	v_cvt_pk_bf16_f32 v147, v148, v149
	v_cvt_pk_bf16_f32 v149, v154, v155
	v_mad_i64_i32 v[154:155], s[8:9], v0, s69, v[150:151]
	v_cvt_pk_bf16_f32 v148, v156, v157
	v_lshl_add_u64 v[154:155], v[154:155], 0, v[152:153]
	global_store_dwordx4 v[154:155], v[146:149], off
	v_pk_mul_f32 v[156:157], v[96:97], v[132:133]
	v_or_b32_e32 v0, 32, v210
	v_pk_mul_f32 v[148:149], v[104:105], v[140:141]
	v_pk_mul_f32 v[146:147], v[102:103], v[138:139]
	s_nop 0
	v_cvt_pk_bf16_f32 v146, v146, v147
	v_cvt_pk_bf16_f32 v147, v148, v149
	v_cvt_pk_bf16_f32 v148, v158, v159
	v_cvt_pk_bf16_f32 v149, v156, v157
	global_store_dwordx4 v[154:155], v[146:149], off offset:256
	v_pk_mul_f32 v[154:155], v[92:93], v[136:137]
	v_pk_mul_f32 v[156:157], v[90:91], v[134:135]
	v_pk_mul_f32 v[148:149], v[100:101], v[144:145]
	v_pk_mul_f32 v[146:147], v[98:99], v[142:143]
	v_pk_mul_f32 v[158:159], v[78:79], v[130:131]
	v_cvt_pk_bf16_f32 v146, v146, v147
	v_cvt_pk_bf16_f32 v147, v148, v149
	v_cvt_pk_bf16_f32 v149, v154, v155
	v_mad_i64_i32 v[154:155], s[8:9], v0, s69, v[150:151]
	v_cvt_pk_bf16_f32 v148, v156, v157
	v_lshl_add_u64 v[154:155], v[154:155], 0, v[152:153]
	global_store_dwordx4 v[154:155], v[146:149], off
	v_pk_mul_f32 v[156:157], v[80:81], v[132:133]
	v_or_b32_e32 v0, 48, v210
	v_pk_mul_f32 v[148:149], v[88:89], v[140:141]
	v_pk_mul_f32 v[146:147], v[86:87], v[138:139]
	s_nop 0
	v_cvt_pk_bf16_f32 v146, v146, v147
	v_cvt_pk_bf16_f32 v147, v148, v149
	v_cvt_pk_bf16_f32 v148, v158, v159
	v_cvt_pk_bf16_f32 v149, v156, v157
	global_store_dwordx4 v[154:155], v[146:149], off offset:256
	v_pk_mul_f32 v[154:155], v[76:77], v[136:137]
	v_pk_mul_f32 v[156:157], v[74:75], v[134:135]
	v_pk_mul_f32 v[148:149], v[84:85], v[144:145]
	v_pk_mul_f32 v[146:147], v[82:83], v[142:143]
	v_pk_mul_f32 v[158:159], v[66:67], v[130:131]
	v_cvt_pk_bf16_f32 v146, v146, v147
	v_cvt_pk_bf16_f32 v147, v148, v149
	v_cvt_pk_bf16_f32 v149, v154, v155
	v_mad_i64_i32 v[154:155], s[8:9], v0, s69, v[150:151]
	v_cvt_pk_bf16_f32 v148, v156, v157
	v_lshl_add_u64 v[154:155], v[154:155], 0, v[152:153]
	global_store_dwordx4 v[154:155], v[146:149], off
	v_pk_mul_f32 v[156:157], v[68:69], v[132:133]
; __device__ __forceinline__ u32x4 pack8(const f32x4& v0, const f32x4& v1) { u32x4 w; w.x = cvt_pk_bf16(v0[0], v0[1]); w.y = cvt_pk_bf16(v0[2], v0[3]); w.z = cvt_pk_bf16(v1[0], v1[1]); w.w = cvt_pk_bf16(v1[2], v1[3]); return w; }
; __device__ __forceinline__ void epi_run(const Epi& E, f32x4 (&acc)[2][2][4][2], const Unit& u, int wr, int wc, int fr, int fq) {
;     ...
; #pragma unroll
;         for (int ai = 0; ai < 2; ++ai)
; #pragma unroll
;             for (int m = 0; m < 4; ++m)
; #pragma unroll
;                 for (int bj = 0; bj < 2; ++bj) *(u32x4*)(E.Z + (size_t)(row0 + ai * 128 + m * 16) * NIN + col0 + bj * 128) = pack8(acc[ai][bj][m][0] * sc[bj][0], acc[ai][bj][m][1] * sc[bj][1]);
	v_add_u32_e32 v0, 0x80, v210
	v_pk_mul_f32 v[148:149], v[72:73], v[140:141]
	v_pk_mul_f32 v[146:147], v[70:71], v[138:139]
	s_nop 0
	v_cvt_pk_bf16_f32 v146, v146, v147
	v_cvt_pk_bf16_f32 v147, v148, v149
	v_cvt_pk_bf16_f32 v148, v158, v159
	v_cvt_pk_bf16_f32 v149, v156, v157
	global_store_dwordx4 v[154:155], v[146:149], off offset:256
	v_pk_mul_f32 v[154:155], v[60:61], v[136:137]
	v_pk_mul_f32 v[156:157], v[58:59], v[134:135]
	v_pk_mul_f32 v[148:149], v[64:65], v[144:145]
	v_pk_mul_f32 v[146:147], v[62:63], v[142:143]
	v_pk_mul_f32 v[158:159], v[50:51], v[130:131]
	v_cvt_pk_bf16_f32 v146, v146, v147
	v_cvt_pk_bf16_f32 v147, v148, v149
	v_cvt_pk_bf16_f32 v149, v154, v155
	v_mad_i64_i32 v[154:155], s[8:9], v0, s69, v[150:151]
	v_cvt_pk_bf16_f32 v148, v156, v157
	v_lshl_add_u64 v[154:155], v[154:155], 0, v[152:153]
	global_store_dwordx4 v[154:155], v[146:149], off
	v_pk_mul_f32 v[156:157], v[52:53], v[132:133]
	v_add_u32_e32 v0, 0x90, v210
	v_pk_mul_f32 v[148:149], v[56:57], v[140:141]
	v_pk_mul_f32 v[146:147], v[54:55], v[138:139]
	s_nop 0
	v_cvt_pk_bf16_f32 v146, v146, v147
	v_cvt_pk_bf16_f32 v147, v148, v149
	v_cvt_pk_bf16_f32 v148, v158, v159
	v_cvt_pk_bf16_f32 v149, v156, v157
	global_store_dwordx4 v[154:155], v[146:149], off offset:256
	v_pk_mul_f32 v[154:155], v[44:45], v[136:137]
	v_pk_mul_f32 v[156:157], v[42:43], v[134:135]
	v_pk_mul_f32 v[148:149], v[48:49], v[144:145]
	v_pk_mul_f32 v[146:147], v[46:47], v[142:143]
	v_pk_mul_f32 v[158:159], v[34:35], v[130:131]
	v_cvt_pk_bf16_f32 v146, v146, v147
	v_cvt_pk_bf16_f32 v147, v148, v149
	v_cvt_pk_bf16_f32 v149, v154, v155
	v_mad_i64_i32 v[154:155], s[8:9], v0, s69, v[150:151]
	v_cvt_pk_bf16_f32 v148, v156, v157
	v_lshl_add_u64 v[154:155], v[154:155], 0, v[152:153]
	global_store_dwordx4 v[154:155], v[146:149], off
	v_pk_mul_f32 v[156:157], v[36:37], v[132:133]
	v_add_u32_e32 v0, 0xa0, v210
	v_pk_mul_f32 v[148:149], v[40:41], v[140:141]
	v_pk_mul_f32 v[146:147], v[38:39], v[138:139]
	s_nop 0
	v_cvt_pk_bf16_f32 v146, v146, v147
	v_cvt_pk_bf16_f32 v147, v148, v149
	v_cvt_pk_bf16_f32 v148, v158, v159
	v_cvt_pk_bf16_f32 v149, v156, v157
	global_store_dwordx4 v[154:155], v[146:149], off offset:256
	v_pk_mul_f32 v[154:155], v[28:29], v[136:137]
	v_pk_mul_f32 v[156:157], v[26:27], v[134:135]
	v_pk_mul_f32 v[148:149], v[32:33], v[144:145]
	v_pk_mul_f32 v[146:147], v[30:31], v[142:143]
	v_pk_mul_f32 v[158:159], v[18:19], v[130:131]
	v_cvt_pk_bf16_f32 v146, v146, v147
	v_cvt_pk_bf16_f32 v147, v148, v149
	v_cvt_pk_bf16_f32 v149, v154, v155
	v_mad_i64_i32 v[154:155], s[8:9], v0, s69, v[150:151]
	v_cvt_pk_bf16_f32 v148, v156, v157
	v_lshl_add_u64 v[154:155], v[154:155], 0, v[152:153]
	global_store_dwordx4 v[154:155], v[146:149], off
	v_pk_mul_f32 v[156:157], v[20:21], v[132:133]
	v_add_u32_e32 v0, 0xb0, v210
	v_pk_mul_f32 v[148:149], v[24:25], v[140:141]
	v_pk_mul_f32 v[146:147], v[22:23], v[138:139]
	v_pk_mul_f32 v[142:143], v[14:15], v[142:143]
	v_cvt_pk_bf16_f32 v146, v146, v147
	v_cvt_pk_bf16_f32 v147, v148, v149
	v_cvt_pk_bf16_f32 v148, v158, v159
	v_cvt_pk_bf16_f32 v149, v156, v157
	global_store_dwordx4 v[154:155], v[146:149], off offset:256
	v_pk_mul_f32 v[144:145], v[16:17], v[144:145]
	s_nop 0
	v_pk_mul_f32 v[146:147], v[12:13], v[136:137]
	v_pk_mul_f32 v[136:137], v[10:11], v[134:135]
	v_cvt_pk_bf16_f32 v134, v142, v143
	v_mad_i64_i32 v[142:143], s[8:9], v0, s69, v[150:151]
	v_cvt_pk_bf16_f32 v135, v144, v145
	v_cvt_pk_bf16_f32 v136, v136, v137
	v_cvt_pk_bf16_f32 v137, v146, v147
	v_lshl_add_u64 v[142:143], v[142:143], 0, v[152:153]
	global_store_dwordx4 v[142:143], v[134:137], off
	s_nop 1
	v_pk_mul_f32 v[134:135], v[8:9], v[140:141]
	v_pk_mul_f32 v[136:137], v[6:7], v[138:139]
	v_pk_mul_f32 v[138:139], v[4:5], v[132:133]
	v_pk_mul_f32 v[132:133], v[2:3], v[130:131]
	v_cvt_pk_bf16_f32 v130, v136, v137
	v_cvt_pk_bf16_f32 v131, v134, v135
	v_cvt_pk_bf16_f32 v132, v132, v133
	v_cvt_pk_bf16_f32 v133, v138, v139
	global_store_dwordx4 v[142:143], v[130:133], off offset:256

; __global__ void __launch_bounds__(512) fwd_kernel(Params p) {
;     ...
;         if (ph + 1 < p.ph_hi && k != 3) { xcd_barrier(xbar); if (p.ph_lo < 0) grid.sync(); }
.LBB0_393:
	s_add_i32 s0, s54, 1
	s_cmp_ge_i32 s0, s55
	v_readlane_b32 s2, v250, 11
	s_cselect_b64 s[0:1], -1, 0
	s_cmp_eq_u32 s2, 3
	s_cselect_b64 s[4:5], -1, 0
	s_or_b64 s[0:1], s[0:1], s[4:5]
	s_and_b64 vcc, exec, s[0:1]
	s_cbranch_vccnz .LBB0_9
	s_cmp_eq_u32 s2, 2
	s_cbranch_scc1 .Lmy_wgsync
	s_cmp_eq_u32 s54, 12
	s_cbranch_scc1 .LBB0_9
	s_waitcnt vmcnt(0)
	s_waitcnt vmcnt(0)
	s_barrier
	s_and_saveexec_b64 s[0:1], s[28:29]
	s_cbranch_execz .LBB0_446
	v_readlane_b32 s2, v251, 31
	s_waitcnt vmcnt(0) expcnt(0) lgkmcnt(0)
	s_nop 0
	v_mov_b32_e32 v0, s2
	ds_read_b32 v3, v0
	v_readlane_b32 s2, v251, 32
	s_waitcnt lgkmcnt(0)
	v_cmp_ne_u32_e32 vcc, 0, v3
	v_mov_b32_e32 v0, s2
	ds_read_b32 v0, v0
	s_cbranch_vccnz .LBB0_410
	s_mov_b32 s2, 1
	s_branch .LBB0_398
